# K bank fix + row-sum as two interleaved 16-long add chains plus a combine (same instruction count and bytes)
# baseline (speedup 1.0000x reference)
.Lattn_back_a:
	ds_read_b128 v[126:129], v186 offset:49152
	ds_read_b128 v[130:133], v186 offset:57344
	v_add_f32_e32 v98, 0, v199
	v_add_f32_e32 v254, v201, v202
	v_add_f32_e32 v98, v205, v98
	v_add_f32_e32 v254, v207, v254
	v_add_f32_e32 v98, v209, v98
	v_add_f32_e32 v254, v211, v254
	s_waitcnt lgkmcnt(1)
	v_mfma_f32_32x32x16_bf16 v[82:97], v[126:129], v[118:121], v[236:251]
	v_add_f32_e32 v98, v213, v98
	v_add_f32_e32 v254, v215, v254
	v_add_f32_e32 v98, v216, v98
	ds_read_b128 v[134:137], v187 offset:49152
	ds_read_b128 v[138:141], v187 offset:57344
	ds_read_b128 v[142:145], v188 offset:49152
	ds_read_b128 v[146:149], v188 offset:57344
	ds_read_b128 v[154:157], v189 offset:49152
	ds_read_b128 v[226:229], v189 offset:57344
	v_add_f32_e32 v254, v217, v254
	v_add_f32_e32 v98, v218, v98
	v_add_f32_e32 v254, v221, v254
	s_waitcnt lgkmcnt(6)
	v_mfma_f32_32x32x16_bf16 v[66:81], v[130:133], v[118:121], v[236:251]
	v_add_f32_e32 v98, v222, v98
	v_add_f32_e32 v254, v223, v254
	v_add_f32_e32 v98, v224, v98
	v_add_f32_e32 v254, v195, v254
	v_add_f32_e32 v98, v196, v98
	v_add_f32_e32 v254, v197, v254
	v_add_f32_e32 v98, v198, v98
	s_waitcnt lgkmcnt(5)
	v_mfma_f32_32x32x16_bf16 v[82:97], v[134:137], v[114:117], v[82:97]
	v_add_f32_e32 v254, v200, v254
	v_add_f32_e32 v98, v203, v98
	v_add_f32_e32 v254, v204, v254
	v_add_f32_e32 v98, v206, v98
	v_add_f32_e32 v254, v208, v254
	v_add_f32_e32 v98, v210, v98
	v_add_f32_e32 v254, v212, v254
	s_waitcnt lgkmcnt(4)
	v_mfma_f32_32x32x16_bf16 v[66:81], v[138:141], v[114:117], v[66:81]
	v_add_f32_e32 v98, v214, v98
	v_add_f32_e32 v254, v150, v254
	v_add_f32_e32 v98, v151, v98
	v_add_f32_e32 v254, v152, v254
	v_add_f32_e32 v98, v153, v98
	v_add_f32_e32 v219, v254, v98
	s_waitcnt lgkmcnt(3)
	v_mfma_f32_32x32x16_bf16 v[82:97], v[142:145], v[110:113], v[82:97]
	v_cvt_pk_bf16_f32 v134, v199, v201
	v_cvt_pk_bf16_f32 v135, v202, v205
	v_cvt_pk_bf16_f32 v136, v207, v209
	v_cvt_pk_bf16_f32 v137, v211, v213
	v_cvt_pk_bf16_f32 v138, v215, v216
	s_waitcnt lgkmcnt(2)
	v_mfma_f32_32x32x16_bf16 v[66:81], v[146:149], v[110:113], v[66:81]
	v_cvt_pk_bf16_f32 v139, v217, v218
	v_cvt_pk_bf16_f32 v140, v221, v222
	v_cvt_pk_bf16_f32 v141, v223, v224
	v_cvt_pk_bf16_f32 v126, v195, v196
	v_cvt_pk_bf16_f32 v127, v197, v198
	v_cvt_pk_bf16_f32 v128, v200, v203
	v_cvt_pk_bf16_f32 v129, v204, v206
	s_waitcnt lgkmcnt(1)
	v_mfma_f32_32x32x16_bf16 v[82:97], v[154:157], v[106:109], v[82:97]
	v_cvt_pk_bf16_f32 v130, v208, v210
	v_cvt_pk_bf16_f32 v131, v212, v214
	v_cvt_pk_bf16_f32 v132, v150, v151
	v_cvt_pk_bf16_f32 v133, v152, v153
	s_waitcnt lgkmcnt(0)
	v_mfma_f32_32x32x16_bf16 v[66:81], v[226:229], v[106:109], v[66:81]
	global_load_dwordx4 v[142:145], v160, s[12:13] offset:2048
	global_load_dwordx4 v[146:149], v252, s[12:13]
	global_load_dwordx4 v[154:157], v161, s[12:13] offset:2048
	s_and_saveexec_b64 s[2:3], s[8:9]
	s_cbranch_execz .LBB0_348
	ds_read2_b32 v[196:197], v194 offset1:1
	ds_read2_b32 v[198:199], v194 offset0:16 offset1:17
	ds_read2_b32 v[200:201], v194 offset0:18 offset1:19
	ds_read2_b32 v[202:203], v194 offset0:24 offset1:25
	ds_read2_b32 v[204:205], v194 offset0:26 offset1:27
	ds_read2_b32 v[206:207], v194 offset0:2 offset1:3
	ds_read2_b32 v[208:209], v194 offset0:8 offset1:9
	ds_read2_b32 v[210:211], v194 offset0:10 offset1:11
	s_waitcnt lgkmcnt(7)
	v_add_f32_e32 v82, v82, v196
	v_add_f32_e32 v83, v83, v197
	s_waitcnt lgkmcnt(3)
	v_add_f32_e32 v96, v96, v204
	v_add_f32_e32 v97, v97, v205
	v_add_f32_e32 v94, v94, v202
	v_add_f32_e32 v95, v95, v203
	v_add_f32_e32 v92, v92, v200
	v_add_f32_e32 v93, v93, v201
	v_add_f32_e32 v90, v90, v198
	v_add_f32_e32 v91, v91, v199
	s_waitcnt lgkmcnt(0)
	v_add_f32_e32 v88, v88, v210
	v_add_f32_e32 v89, v89, v211
	v_add_f32_e32 v86, v86, v208
	v_add_f32_e32 v87, v87, v209
	v_add_f32_e32 v84, v84, v206
	v_add_f32_e32 v85, v85, v207
	ds_read2_b32 v[196:197], v194 offset0:48 offset1:49
	ds_read2_b32 v[198:199], v194 offset0:50 offset1:51
	ds_read2_b32 v[200:201], v194 offset0:56 offset1:57
	ds_read2_b32 v[202:203], v194 offset0:58 offset1:59
	ds_read2_b32 v[204:205], v194 offset0:32 offset1:33
	ds_read2_b32 v[206:207], v194 offset0:34 offset1:35
	ds_read2_b32 v[208:209], v194 offset0:40 offset1:41
	ds_read2_b32 v[210:211], v194 offset0:42 offset1:43
	s_waitcnt lgkmcnt(4)
	v_add_f32_e32 v80, v80, v202
	v_add_f32_e32 v81, v81, v203
	v_add_f32_e32 v78, v78, v200
	v_add_f32_e32 v79, v79, v201
	v_add_f32_e32 v76, v76, v198
	v_add_f32_e32 v77, v77, v199
	v_add_f32_e32 v74, v74, v196
	v_add_f32_e32 v75, v75, v197
	s_waitcnt lgkmcnt(0)
	v_add_f32_e32 v72, v72, v210
	v_add_f32_e32 v73, v73, v211
	v_add_f32_e32 v70, v70, v208
	v_add_f32_e32 v71, v71, v209
	v_add_f32_e32 v68, v68, v206
	v_add_f32_e32 v69, v69, v207
	v_add_f32_e32 v66, v66, v204
	v_add_f32_e32 v67, v67, v205

.Lattn_back_b:
	ds_read_b128 v[126:129], v186 offset:32768
	ds_read_b128 v[130:133], v186 offset:40960
	ds_read_b128 v[134:137], v187 offset:32768
	ds_read_b128 v[138:141], v187 offset:40960
	v_add_f32_e32 v98, 0, v212
	v_add_f32_e32 v254, v214, v216
	v_add_f32_e32 v98, v218, v98
	v_add_f32_e32 v254, v204, v254
	v_add_f32_e32 v98, v206, v98
	v_add_f32_e32 v254, v208, v254
	v_add_f32_e32 v98, v210, v98
	s_waitcnt lgkmcnt(3)
	v_mfma_f32_32x32x16_bf16 v[82:97], v[126:129], v[118:121], v[236:251]
	v_add_f32_e32 v254, v196, v254
	v_add_f32_e32 v98, v198, v98
	v_add_f32_e32 v254, v200, v254
	v_add_f32_e32 v98, v202, v98
	v_add_f32_e32 v254, v222, v254
	v_add_f32_e32 v98, v224, v98
	v_add_f32_e32 v254, v227, v254
	s_waitcnt lgkmcnt(2)
	v_mfma_f32_32x32x16_bf16 v[66:81], v[130:133], v[118:121], v[236:251]
	v_add_f32_e32 v98, v229, v98
	ds_read_b128 v[126:129], v188 offset:32768
	ds_read_b128 v[142:145], v188 offset:40960
	ds_read_b128 v[146:149], v189 offset:32768
	ds_read_b128 v[154:157], v189 offset:40960
	v_add_f32_e32 v254, v213, v254
	v_add_f32_e32 v98, v215, v98
	v_add_f32_e32 v254, v217, v254
	v_add_f32_e32 v98, v221, v98
	v_add_f32_e32 v254, v205, v254
	s_waitcnt lgkmcnt(5)
	v_mfma_f32_32x32x16_bf16 v[82:97], v[134:137], v[114:117], v[82:97]
	v_add_f32_e32 v98, v207, v98
	v_add_f32_e32 v254, v209, v254
	v_add_f32_e32 v98, v211, v98
	v_add_f32_e32 v254, v197, v254
	v_add_f32_e32 v98, v199, v98
	v_add_f32_e32 v254, v201, v254
	v_add_f32_e32 v98, v203, v98
	s_waitcnt lgkmcnt(4)
	v_mfma_f32_32x32x16_bf16 v[66:81], v[138:141], v[114:117], v[66:81]
	v_add_f32_e32 v254, v223, v254
	v_add_f32_e32 v98, v226, v98
	v_add_f32_e32 v254, v228, v254
	v_add_f32_e32 v98, v230, v98
	v_add_f32_e32 v98, v254, v98
	s_waitcnt lgkmcnt(3)
	v_mfma_f32_32x32x16_bf16 v[82:97], v[126:129], v[110:113], v[82:97]
	v_cvt_pk_bf16_f32 v150, v212, v214
	v_cvt_pk_bf16_f32 v151, v216, v218
	v_cvt_pk_bf16_f32 v152, v204, v206
	v_cvt_pk_bf16_f32 v153, v208, v210
	v_cvt_pk_bf16_f32 v134, v196, v198
	v_cvt_pk_bf16_f32 v135, v200, v202
	v_cvt_pk_bf16_f32 v136, v222, v224
	s_waitcnt lgkmcnt(2)
	v_mfma_f32_32x32x16_bf16 v[66:81], v[142:145], v[110:113], v[66:81]
	v_cvt_pk_bf16_f32 v137, v227, v229
	v_cvt_pk_bf16_f32 v130, v213, v215
	v_cvt_pk_bf16_f32 v131, v217, v221
	v_cvt_pk_bf16_f32 v132, v205, v207
	v_cvt_pk_bf16_f32 v133, v209, v211
	v_cvt_pk_bf16_f32 v126, v197, v199
	v_cvt_pk_bf16_f32 v127, v201, v203
	s_waitcnt lgkmcnt(1)
	v_mfma_f32_32x32x16_bf16 v[82:97], v[146:149], v[106:109], v[82:97]
	v_cvt_pk_bf16_f32 v128, v223, v226
	v_cvt_pk_bf16_f32 v129, v228, v230
	s_waitcnt lgkmcnt(0)
	v_mfma_f32_32x32x16_bf16 v[66:81], v[154:157], v[106:109], v[66:81]
	s_add_u32 s100, s12, 0xa0000
	s_addc_u32 s101, s13, 0
	global_load_dwordx4 v[138:141], v160, s[100:101] offset:2048
	global_load_dwordx4 v[142:145], v252, s[100:101]
	global_load_dwordx4 v[154:157], v161, s[100:101] offset:2048
	s_add_u32 s12, s12, 0x140000
	s_addc_u32 s13, s13, 0
	s_and_saveexec_b64 s[2:3], s[8:9]
	s_cbranch_execz .LBB0_345
	ds_read2_b32 v[196:197], v194 offset0:64 offset1:65
	ds_read2_b32 v[198:199], v194 offset0:80 offset1:81
	ds_read2_b32 v[200:201], v194 offset0:82 offset1:83
	ds_read2_b32 v[202:203], v194 offset0:88 offset1:89
	ds_read2_b32 v[204:205], v194 offset0:90 offset1:91
	ds_read2_b32 v[206:207], v194 offset0:66 offset1:67
	ds_read2_b32 v[208:209], v194 offset0:72 offset1:73
	ds_read2_b32 v[210:211], v194 offset0:74 offset1:75
	s_waitcnt lgkmcnt(7)
	v_add_f32_e32 v82, v82, v196
	v_add_f32_e32 v83, v83, v197
	s_waitcnt lgkmcnt(3)
	v_add_f32_e32 v96, v96, v204
	v_add_f32_e32 v97, v97, v205
	v_add_f32_e32 v94, v94, v202
	v_add_f32_e32 v95, v95, v203
	v_add_f32_e32 v92, v92, v200
	v_add_f32_e32 v93, v93, v201
	v_add_f32_e32 v90, v90, v198
	v_add_f32_e32 v91, v91, v199
	s_waitcnt lgkmcnt(0)
	v_add_f32_e32 v88, v88, v210
	v_add_f32_e32 v89, v89, v211
	v_add_f32_e32 v86, v86, v208
	v_add_f32_e32 v87, v87, v209
	v_add_f32_e32 v84, v84, v206
	v_add_f32_e32 v85, v85, v207
	ds_read2_b32 v[196:197], v194 offset0:112 offset1:113
	ds_read2_b32 v[198:199], v194 offset0:114 offset1:115
	ds_read2_b32 v[200:201], v194 offset0:120 offset1:121
	ds_read2_b32 v[202:203], v194 offset0:122 offset1:123
	ds_read2_b32 v[204:205], v194 offset0:96 offset1:97
	ds_read2_b32 v[206:207], v194 offset0:98 offset1:99
	ds_read2_b32 v[208:209], v194 offset0:104 offset1:105
	ds_read2_b32 v[210:211], v194 offset0:106 offset1:107
	s_waitcnt lgkmcnt(4)
	v_add_f32_e32 v80, v80, v202
	v_add_f32_e32 v81, v81, v203
	v_add_f32_e32 v78, v78, v200
	v_add_f32_e32 v79, v79, v201
	v_add_f32_e32 v76, v76, v198
	v_add_f32_e32 v77, v77, v199
	v_add_f32_e32 v74, v74, v196
	v_add_f32_e32 v75, v75, v197
	s_waitcnt lgkmcnt(0)
	v_add_f32_e32 v72, v72, v210
	v_add_f32_e32 v73, v73, v211
	v_add_f32_e32 v70, v70, v208
	v_add_f32_e32 v71, v71, v209
	v_add_f32_e32 v68, v68, v206
	v_add_f32_e32 v69, v69, v207
	v_add_f32_e32 v66, v66, v204
	v_add_f32_e32 v67, v67, v205
	s_branch .LBB0_345
